# attention unit: cmp-branch k_gain loads issued together with the Q loads (were issued and waited later on their own)
# baseline (speedup 1.0000x reference)
; #define LAS __attribute__((address_space(3)))
; DI void unit(const int wv, const Params& p, int l, int b, int g, int qt, LAS unsigned char* lds) {
;     ...
;     const int lane = tid & 63, wave = tid >> 6, rr = lane & 31, h = lane >> 5, r = lane & 3, tl = rr >> 2;
;     const bf16_t* P = (const bf16_t*)(p.ws + WS_P); const bf16_t* Vt = (const bf16_t*)(p.ws + WS_VT);
;     const int tok_l = 8 * wave + tl, t_tok = 64 * qt + tok_l, head = g * 4 + r; const unsigned m = (unsigned)(b * T + t_tok);
;     LAS float* imp = (LAS float*)(lds + IMP_OFF); LAS unsigned long long* selw = (LAS unsigned long long*)(lds + SEL_OFF); LAS unsigned long long* uniw = (LAS unsigned long long*)(lds + UNI_OFF);
;     bf16x8 qf[8];
;     { const bf16_t* qp = P + (size_t)(m * (unsigned)PWID + PC_Q + head * 128 + 8 * h);
; #pragma unroll
;       for (int ks = 0; ks < 8; ++ks) qf[ks] = *(const bf16x8*)(qp + 16 * ks); }
;     const float sc_l2 = 0.08838834764831845f * 1.44269504f;
;     const float sl_l2 = __builtin_amdgcn_exp2f(-(float)(head + 1)) * 1.44269504f;
;     float qn;
;     { float s = 0.f;
; #pragma unroll
;       for (int ks = 0; ks < 8; ++ks)
; #pragma unroll
;           for (int e = 0; e < 8; ++e) { const float f = bf2f((unsigned short)qf[ks][e]); s += f * f; }
;       s += __shfl_xor(s, 32); qn = sqrtf(s) * (11.313708499f * 1.02f); }
;     ...
;     for (int i = tid; i < 64 * 64; i += 512) imp[i] = 0.f;
.LBB0_520:
	s_and_b64 vcc, exec, s[0:1]
	s_cbranch_vccz .LBB0_505
	s_mov_b32 s0, -1
	s_bfe_u32 s76, s18, 0x60002
	v_mbcnt_lo_u32_b32 v0, s0, 0
	v_mbcnt_hi_u32_b32 v0, s0, v0
	s_xor_b32 s85, s76, 63
	s_and_b32 s88, s18, 3
	v_add_u32_e32 v0, s64, v0
	s_cmpk_lt_i32 s18, 0x100
	s_cselect_b64 s[2:3], -1, 0
	v_ashrrev_i32_e32 v191, 6, v0
	v_lshrrev_b32_e32 v1, 2, v0
	v_lshlrev_b32_e32 v192, 3, v191
	v_and_or_b32 v190, v1, 7, v192
	v_writelane_b32 v255, s2, 10
	s_and_b64 s[0:1], s[2:3], exec
	v_lshl_add_u32 v213, s85, 6, v190
	s_cselect_b32 s0, 4, 0
	v_bfe_u32 v211, v0, 5, 1
	v_and_or_b32 v194, v0, 3, s0
	v_lshl_add_u32 v212, s88, 12, v213
	s_movk_i32 s0, 0xc00
	v_mul_lo_u32 v1, v212, s0
	v_lshlrev_b32_e32 v210, 7, v194
	v_lshlrev_b32_e32 v2, 3, v211
	v_or3_b32 v1, v1, v2, v210
	v_add_u32_e32 v160, 0x400, v1
	v_lshl_add_u64 v[2:3], v[160:161], 1, s[80:81]
	global_load_dwordx4 v[112:115], v[2:3], off
	global_load_dwordx4 v[116:119], v[2:3], off offset:32
	global_load_dwordx4 v[120:123], v[2:3], off offset:64
	global_load_dwordx4 v[124:127], v[2:3], off offset:96
	global_load_dwordx4 v[128:131], v[2:3], off offset:128
	global_load_dwordx4 v[132:135], v[2:3], off offset:160
	global_load_dwordx4 v[136:139], v[2:3], off offset:192
	global_load_dwordx4 v[140:143], v[2:3], off offset:224
	v_mbcnt_lo_u32_b32 v207, -1, 0
	v_mbcnt_hi_u32_b32 v207, -1, v207
	v_readlane_b32 s98, v255, 9
	v_readlane_b32 s100, v253, 14
	v_readlane_b32 s101, v253, 15
	s_nop 1
	v_or_b32_e32 v207, s98, v207
	v_lshlrev_b32_e32 v207, 2, v207
	s_nop 3
	global_load_dword v208, v207, s[100:101] offset:256
	global_load_dword v207, v207, s[100:101]
	s_movk_i32 s0, 0x1000
	v_writelane_b32 v255, s3, 11
	s_waitcnt vmcnt(0)
	v_and_b32_e32 v1, 0xffff0000, v112
	v_lshlrev_b32_e32 v2, 16, v112
	v_mul_f32_e32 v1, v1, v1
	v_fmac_f32_e32 v1, v2, v2
	v_lshlrev_b32_e32 v2, 16, v113
	v_fmac_f32_e32 v1, v2, v2
	v_and_b32_e32 v2, 0xffff0000, v113
	v_fmac_f32_e32 v1, v2, v2
	v_lshlrev_b32_e32 v2, 16, v114
	v_fmac_f32_e32 v1, v2, v2
	v_and_b32_e32 v2, 0xffff0000, v114
	v_fmac_f32_e32 v1, v2, v2
	v_lshlrev_b32_e32 v2, 16, v115
	v_fmac_f32_e32 v1, v2, v2
	v_and_b32_e32 v2, 0xffff0000, v115
	v_fmac_f32_e32 v1, v2, v2
	v_lshlrev_b32_e32 v2, 16, v116
	v_fmac_f32_e32 v1, v2, v2
	v_and_b32_e32 v2, 0xffff0000, v116
	v_fmac_f32_e32 v1, v2, v2
	v_lshlrev_b32_e32 v2, 16, v117
	v_fmac_f32_e32 v1, v2, v2
	v_and_b32_e32 v2, 0xffff0000, v117
	v_fmac_f32_e32 v1, v2, v2
	v_lshlrev_b32_e32 v2, 16, v118
	v_fmac_f32_e32 v1, v2, v2
	v_and_b32_e32 v2, 0xffff0000, v118
	v_fmac_f32_e32 v1, v2, v2
	v_lshlrev_b32_e32 v2, 16, v119
	v_fmac_f32_e32 v1, v2, v2
	v_and_b32_e32 v2, 0xffff0000, v119
	v_fmac_f32_e32 v1, v2, v2
	v_lshlrev_b32_e32 v2, 16, v120
	v_fmac_f32_e32 v1, v2, v2
	v_and_b32_e32 v2, 0xffff0000, v120
	v_fmac_f32_e32 v1, v2, v2
	v_lshlrev_b32_e32 v2, 16, v121
	v_fmac_f32_e32 v1, v2, v2
	v_and_b32_e32 v2, 0xffff0000, v121
	v_fmac_f32_e32 v1, v2, v2
	v_lshlrev_b32_e32 v2, 16, v122
	v_fmac_f32_e32 v1, v2, v2
	v_and_b32_e32 v2, 0xffff0000, v122
	v_fmac_f32_e32 v1, v2, v2
	v_lshlrev_b32_e32 v2, 16, v123
	v_fmac_f32_e32 v1, v2, v2
	v_and_b32_e32 v2, 0xffff0000, v123
	v_fmac_f32_e32 v1, v2, v2
	v_lshlrev_b32_e32 v2, 16, v124
	v_fmac_f32_e32 v1, v2, v2
	v_and_b32_e32 v2, 0xffff0000, v124
	v_fmac_f32_e32 v1, v2, v2
	v_lshlrev_b32_e32 v2, 16, v125
	v_fmac_f32_e32 v1, v2, v2
	v_and_b32_e32 v2, 0xffff0000, v125
	v_fmac_f32_e32 v1, v2, v2
	v_lshlrev_b32_e32 v2, 16, v126
	v_fmac_f32_e32 v1, v2, v2
	v_and_b32_e32 v2, 0xffff0000, v126
	v_fmac_f32_e32 v1, v2, v2
	v_lshlrev_b32_e32 v2, 16, v127
	v_fmac_f32_e32 v1, v2, v2
	v_and_b32_e32 v2, 0xffff0000, v127
	v_fmac_f32_e32 v1, v2, v2
	v_lshlrev_b32_e32 v2, 16, v128
	v_fmac_f32_e32 v1, v2, v2
	v_and_b32_e32 v2, 0xffff0000, v128
	v_fmac_f32_e32 v1, v2, v2
	v_lshlrev_b32_e32 v2, 16, v129
	v_fmac_f32_e32 v1, v2, v2
	v_and_b32_e32 v2, 0xffff0000, v129
	v_fmac_f32_e32 v1, v2, v2
	v_lshlrev_b32_e32 v2, 16, v130
	v_fmac_f32_e32 v1, v2, v2
	v_and_b32_e32 v2, 0xffff0000, v130
	v_fmac_f32_e32 v1, v2, v2
	v_lshlrev_b32_e32 v2, 16, v131
	v_fmac_f32_e32 v1, v2, v2
	v_and_b32_e32 v2, 0xffff0000, v131
	v_fmac_f32_e32 v1, v2, v2
	v_lshlrev_b32_e32 v2, 16, v132
	v_fmac_f32_e32 v1, v2, v2
	v_and_b32_e32 v2, 0xffff0000, v132
	v_fmac_f32_e32 v1, v2, v2
	v_lshlrev_b32_e32 v2, 16, v133
	v_fmac_f32_e32 v1, v2, v2
	v_and_b32_e32 v2, 0xffff0000, v133
	v_fmac_f32_e32 v1, v2, v2
	v_lshlrev_b32_e32 v2, 16, v134
	v_fmac_f32_e32 v1, v2, v2
	v_and_b32_e32 v2, 0xffff0000, v134
	v_fmac_f32_e32 v1, v2, v2
	v_lshlrev_b32_e32 v2, 16, v135
	v_fmac_f32_e32 v1, v2, v2
	v_and_b32_e32 v2, 0xffff0000, v135
	v_fmac_f32_e32 v1, v2, v2
	v_lshlrev_b32_e32 v2, 16, v136
	v_fmac_f32_e32 v1, v2, v2
	v_and_b32_e32 v2, 0xffff0000, v136
	v_fmac_f32_e32 v1, v2, v2
	v_lshlrev_b32_e32 v2, 16, v137
	v_fmac_f32_e32 v1, v2, v2
	v_and_b32_e32 v2, 0xffff0000, v137
	v_fmac_f32_e32 v1, v2, v2
	v_lshlrev_b32_e32 v2, 16, v138
	v_fmac_f32_e32 v1, v2, v2
	v_and_b32_e32 v2, 0xffff0000, v138
	v_fmac_f32_e32 v1, v2, v2
	v_lshlrev_b32_e32 v2, 16, v139
	v_fmac_f32_e32 v1, v2, v2
	v_and_b32_e32 v2, 0xffff0000, v139
	v_fmac_f32_e32 v1, v2, v2
	v_lshlrev_b32_e32 v2, 16, v140
	v_fmac_f32_e32 v1, v2, v2
	v_and_b32_e32 v2, 0xffff0000, v140
	v_fmac_f32_e32 v1, v2, v2
	v_lshlrev_b32_e32 v2, 16, v141
	v_fmac_f32_e32 v1, v2, v2
	v_and_b32_e32 v2, 0xffff0000, v141
	v_fmac_f32_e32 v1, v2, v2
	v_lshlrev_b32_e32 v2, 16, v142
	v_fmac_f32_e32 v1, v2, v2
	v_and_b32_e32 v2, 0xffff0000, v142
	v_fmac_f32_e32 v1, v2, v2
	v_lshlrev_b32_e32 v2, 16, v143
	v_fmac_f32_e32 v1, v2, v2
	v_and_b32_e32 v2, 0xffff0000, v143
	v_fmac_f32_e32 v1, v2, v2
	v_xor_b32_e32 v2, 32, v201
	v_cmp_lt_i32_e32 vcc, v2, v202
	s_nop 1
	v_cndmask_b32_e32 v2, v201, v2, vcc
	v_lshlrev_b32_e32 v214, 2, v2
	ds_bpermute_b32 v2, v214, v1
	v_cmp_gt_i32_e32 vcc, s0, v0
	s_and_saveexec_b64 s[0:1], vcc
	s_cbranch_execz .LBB0_524
	v_readlane_b32 s2, v254, 35
	v_add_u32_e32 v3, 0xfffffe00, v0
	s_nop 0
	v_lshl_add_u32 v4, v0, 2, s2
	s_mov_b64 s[2:3], 0

; #define LAS __attribute__((address_space(3)))
; #define ATT_LOAD(j) do { _Pragma("unroll") for (int _i = 0; _i < 2; ++_i) { const int _c = tid + 512 * _i; \
;         kr[_i] = *(const u32x4*)(kbase + (size_t)(64 * (j) + (_c >> 4)) * ldk + (_c & 15) * 16); \
;         if (MODE != 0) vr[_i] = *(const u32x4*)(vbase + (size_t)(_c >> 3) * ldv + (size_t)(j) * 128 + (_c & 7) * 16); } } while (0)
; #define ATT_STORE(LB) do { _Pragma("unroll") for (int _i = 0; _i < 2; ++_i) { const int _c = tid + 512 * _i; \
;         *(LAS u32x4*)((LB) + K_OFF + (_c >> 4) * KST + (_c & 15) * 16) = kr[_i]; \
;         if (MODE != 0) { LAS u32x2* _d = (LAS u32x2*)((LB) + V_OFF + (_c >> 3) * VST + (_c & 7) * 16); _d[0] = (u32x2){vr[_i].x, vr[_i].y}; _d[1] = (u32x2){vr[_i].z, vr[_i].w}; } } } while (0)
; #define ATT_GK(k) wave_max(fmaxf(fabsf(p.k_gain[(l * 3 + (k)) * 128 + lane]), fabsf(p.k_gain[(l * 3 + (k)) * 128 + lane + 64])))
; template <int MODE> ...
;     ...
;     int j = __builtin_ctzll(tiles); tiles &= tiles - 1;
;     LAS unsigned char* const lds0 = lds;
;     ATT_LOAD(j); ATT_STORE(lds0);
;     __syncthreads();
; DI void unit(const int wv, const Params& p, int l, int b, int g, int qt, LAS unsigned char* lds) {
;     ...
;     const float sl_l2 = __builtin_amdgcn_exp2f(-(float)(head + 1)) * 1.44269504f;
;     float qn;
;     { float s = 0.f;
; #pragma unroll
;       for (int ks = 0; ks < 8; ++ks)
; #pragma unroll
;           for (int e = 0; e < 8; ++e) { const float f = bf2f((unsigned short)qf[ks][e]); s += f * f; }
;       s += __shfl_xor(s, 32); qn = sqrtf(s) * (11.313708499f * 1.02f); }
;     ...
;     for (int i = tid; i < 64 * 64; i += 512) imp[i] = 0.f;
;     __syncthreads();
;     f32x16 O[4]; LAS unsigned* outp = (LAS unsigned*)(lds + OUT_OFF) + wave * 2048 + lane;
;     const char* kc_base = (const char*)(p.ws + WS_KCMP) + ((size_t)b * 2 + g) * 256 * 256;
;     const char* vc_base = (const char*)(p.ws + WS_VCMP) + ((size_t)b * 2 + g) * 128 * 512;
;     const int nct = (4 * qt + 2) / 64 + 1;
;     const unsigned long long ctiles = (1ull << nct) - 1ull;
;     float l_c = 0.f;
;     branch<0>(wv, lds, qf, kc_base, 256, vc_base, 512, ctiles, ~0ull, 0ull, qt, t_tok, sc_l2, sl_l2, qn * ATT_GK(0), 0ull, 0.f, l_c, O, imp + tok_l * 64);
.LBB0_524:
	s_or_b64 exec, exec, s[0:1]
	v_and_b32_e32 v193, 63, v0
	v_add_u32_e32 v0, 1, v194
	v_cvt_f32_ubyte0_e32 v0, v0
	v_exp_f32_e64 v0, -v0
	s_mov_b32 s0, 0xf800000
	s_lshl_b32 s2, s88, 17
	v_readlane_b32 s4, v253, 0
	v_mul_f32_e32 v169, 0x3fb8aa3b, v0
	s_waitcnt lgkmcnt(0)
	v_add_f32_e32 v0, v1, v2
	v_cmp_gt_f32_e32 vcc, s0, v0
	v_mul_f32_e32 v1, 0x4f800000, v0
	v_readlane_b32 s18, v253, 14
	v_cndmask_b32_e32 v0, v0, v1, vcc
	v_sqrt_f32_e32 v1, v0
	v_readlane_b32 s19, v253, 15
	s_barrier
	v_add_u32_e32 v2, -1, v1
	v_fma_f32 v3, -v2, v1, v0
	v_cmp_ge_f32_e64 s[0:1], 0, v3
	v_add_u32_e32 v3, 1, v1
	s_nop 0
	v_cndmask_b32_e64 v2, v1, v2, s[0:1]
	v_fma_f32 v1, -v3, v1, v0
	v_cmp_lt_f32_e64 s[0:1], 0, v1
	s_movk_i32 s4, 0x110
	v_readlane_b32 s6, v253, 2
	v_cndmask_b32_e64 v1, v2, v3, s[0:1]
	v_readlane_b32 s0, v255, 10
	v_readlane_b32 s1, v255, 11
	s_and_b64 s[0:1], s[0:1], exec
	v_mul_f32_e32 v2, 0x37800000, v1
	s_cselect_b32 s0, 0x10000, 0
	v_cndmask_b32_e32 v1, v1, v2, vcc
	v_mov_b32_e32 v2, 0x260
	s_or_b32 s86, s0, s2
	v_readlane_b32 s2, v255, 9
	v_cmp_class_f32_e32 vcc, v0, v2
	v_readlane_b32 s0, v254, 3
	v_or_b32_e32 v160, s2, v193
	v_cndmask_b32_e32 v0, v1, v0, vcc
	v_lshl_add_u64 v[40:41], v[160:161], 2, s[18:19]
	v_mul_f32_e32 v215, 0x4138a3c4, v0
	v_mov_b32_e32 v0, v207
	v_mov_b32_e32 v1, v208
	v_cmp_lt_i32_e32 vcc, v203, v202
	s_mov_b32 s2, -1
	v_readlane_b32 s1, v254, 4
	s_add_u32 s74, s0, s86
	s_addc_u32 s75, s1, 0
	s_lshr_b32 s0, s85, 4
	s_add_i32 s0, s0, 1
	s_lshl_b64 s[0:1], -1, s0
	v_readlane_b32 s7, v253, 3
	s_mov_b32 s81, s65
	s_mov_b64 s[70:71], s[72:73]
	s_mov_b64 s[82:83], s[66:67]
	v_mov_b32_e32 v48, 0
	s_mov_b32 s92, 0
	s_mov_b32 s80, s64
	v_subrev_u32_e32 v195, 31, v213
	v_mov_b32_e32 v168, v169
	v_mov_b32_e32 v170, v169
	v_mov_b32_e32 v171, v169
	v_mov_b32_e32 v172, v169
	v_mov_b32_e32 v173, v169
	v_mov_b32_e32 v174, v169
	v_mov_b32_e32 v175, v169
	v_mov_b32_e32 v176, v169
	v_mov_b32_e32 v177, v169
	v_mov_b32_e32 v178, v169
	v_mov_b32_e32 v179, v169
	v_mov_b32_e32 v180, v169
	v_mov_b32_e32 v181, v169
	v_mov_b32_e32 v182, v169
	v_mov_b32_e32 v183, v169
	v_mov_b32_e32 v184, v169
	v_mov_b32_e32 v185, v169
	v_readlane_b32 s5, v253, 1
	v_readlane_b32 s8, v253, 4
	v_readlane_b32 s9, v253, 5
	v_readlane_b32 s10, v253, 6
	v_readlane_b32 s11, v253, 7
	v_readlane_b32 s12, v253, 8
	v_readlane_b32 s13, v253, 9
	v_readlane_b32 s14, v253, 10
	v_readlane_b32 s15, v253, 11
	v_readlane_b32 s16, v253, 12
	v_readlane_b32 s17, v253, 13
	s_waitcnt vmcnt(1)
	v_max_f32_e64 v0, |v0|, |v0|
	s_waitcnt vmcnt(0)
	v_max_f32_e64 v1, |v1|, |v1|
	v_max_f32_e32 v0, v0, v1
	v_cndmask_b32_e32 v1, v201, v203, vcc
	v_lshlrev_b32_e32 v216, 2, v1
	ds_bpermute_b32 v1, v216, v0
	v_cmp_lt_i32_e32 vcc, v204, v202
	s_waitcnt lgkmcnt(0)
	v_max_f32_e32 v1, v1, v1
	v_max_f32_e32 v0, v0, v1
	v_cndmask_b32_e32 v1, v201, v204, vcc
	v_lshlrev_b32_e32 v217, 2, v1
	ds_bpermute_b32 v1, v217, v0
	v_cmp_lt_i32_e32 vcc, v205, v202
	s_waitcnt lgkmcnt(0)
	v_max_f32_e32 v1, v1, v1
	v_max_f32_e32 v0, v0, v1
	v_cndmask_b32_e32 v1, v201, v205, vcc
	v_lshlrev_b32_e32 v218, 2, v1
	ds_bpermute_b32 v1, v218, v0
	v_cmp_lt_i32_e32 vcc, v206, v202
	s_waitcnt lgkmcnt(0)
	v_max_f32_e32 v1, v1, v1
	v_max_f32_e32 v0, v0, v1
	v_cndmask_b32_e32 v1, v201, v206, vcc
	v_lshlrev_b32_e32 v219, 2, v1
	ds_bpermute_b32 v1, v219, v0
	s_waitcnt lgkmcnt(0)
	v_max_f32_e32 v1, v1, v1
	v_max_f32_e32 v0, v0, v1
	v_xor_b32_e32 v1, 16, v201
	v_cmp_lt_i32_e32 vcc, v1, v202
	s_nop 1
	v_cndmask_b32_e32 v1, v201, v1, vcc
	v_lshlrev_b32_e32 v220, 2, v1
	ds_bpermute_b32 v1, v220, v0
	s_waitcnt lgkmcnt(0)
	v_max_f32_e32 v1, v1, v1
	v_max_f32_e32 v0, v0, v1
	ds_bpermute_b32 v1, v214, v0
	s_waitcnt lgkmcnt(0)
	v_max_f32_e32 v1, v1, v1
	v_max_f32_e32 v0, v0, v1
	v_mul_f32_e32 v49, v215, v0
	v_mbcnt_lo_u32_b32 v0, s2, 0
	v_mbcnt_hi_u32_b32 v0, s2, v0
	v_add_u32_e32 v2, s64, v0
	s_sub_u32 s2, 14, s0
	v_lshlrev_b32_e32 v0, 4, v2
	v_ashrrev_i32_e32 v44, 4, v2
	v_and_b32_e32 v160, 0xf0, v0
	v_ashrrev_i32_e32 v45, 31, v44
	v_lshl_add_u64 v[42:43], s[74:75], 0, v[160:161]
	v_lshlrev_b64 v[0:1], 8, v[44:45]
	v_lshl_add_u64 v[0:1], v[42:43], 0, v[0:1]
	global_load_dwordx4 v[32:35], v[0:1], off
	v_add_u32_e32 v0, 0x200, v2
	v_ashrrev_i32_e32 v46, 4, v0
	v_ashrrev_i32_e32 v47, 31, v46
	v_lshlrev_b64 v[0:1], 8, v[46:47]
	v_lshl_add_u64 v[0:1], v[42:43], 0, v[0:1]
	global_load_dwordx4 v[36:39], v[0:1], off
	v_add_u32_e32 v45, 0, v160
	v_mul_lo_u32 v47, v44, s4
	v_add_u32_e32 v1, v45, v47
	v_mul_lo_u32 v50, v46, s4
	s_subb_u32 s3, 0, s1
	v_bfe_u32 v0, v2, 5, 1
	s_andn2_b64 s[6:7], s[2:3], s[0:1]
	v_lshlrev_b32_e32 v51, 6, v0
	s_mov_b32 s4, 0
	s_mov_b64 s[2:3], s[6:7]
	s_waitcnt vmcnt(1)
	ds_write_b128 v1, v[32:35]
	v_add_u32_e32 v1, v45, v50
	s_waitcnt vmcnt(0)
	ds_write_b128 v1, v[36:39]
	v_and_b32_e32 v1, 31, v2
	v_mul_u32_u24_e32 v1, 0x110, v1
	v_lshlrev_b32_e32 v2, 4, v0
	v_add3_u32 v52, 0, v1, v2
	s_waitcnt lgkmcnt(0)
	s_barrier

; __global__ void __launch_bounds__(512, 2) mega(Params p) {
	.amdhsa_kernel _Z4mega6Params
		.amdhsa_group_segment_fixed_size 0
		.amdhsa_private_segment_fixed_size 0
		.amdhsa_kernarg_size 408
		.amdhsa_user_sgpr_count 2
		.amdhsa_user_sgpr_dispatch_ptr 0
		.amdhsa_user_sgpr_queue_ptr 0
		.amdhsa_user_sgpr_kernarg_segment_ptr 1
		.amdhsa_user_sgpr_dispatch_id 0
		.amdhsa_user_sgpr_kernarg_preload_length 0
		.amdhsa_user_sgpr_kernarg_preload_offset 0
		.amdhsa_user_sgpr_private_segment_size 0
		.amdhsa_uses_dynamic_stack 0
		.amdhsa_enable_private_segment 0
		.amdhsa_system_sgpr_workgroup_id_x 1
		.amdhsa_system_sgpr_workgroup_id_y 0
		.amdhsa_system_sgpr_workgroup_id_z 0
		.amdhsa_system_sgpr_workgroup_info 0
		.amdhsa_system_vgpr_workitem_id 2
		.amdhsa_next_free_vgpr 256
		.amdhsa_next_free_sgpr 102
		.amdhsa_accum_offset 256
		.amdhsa_reserve_vcc 1
		.amdhsa_float_round_mode_32 0
		.amdhsa_float_round_mode_16_64 0
		.amdhsa_float_denorm_mode_32 3
		.amdhsa_float_denorm_mode_16_64 3
		.amdhsa_dx10_clamp 1
		.amdhsa_ieee_mode 1
		.amdhsa_fp16_overflow 0
		.amdhsa_tg_split 0
		.amdhsa_exception_fp_ieee_invalid_op 0
		.amdhsa_exception_fp_denorm_src 0
		.amdhsa_exception_fp_ieee_div_zero 0
		.amdhsa_exception_fp_ieee_overflow 0
		.amdhsa_exception_fp_ieee_underflow 0
		.amdhsa_exception_fp_ieee_inexact 0
		.amdhsa_exception_int_div_zero 0
	.end_amdhsa_kernel
